# p->PB fast path only (prologue de-serialisation)
# baseline (speedup 1.0000x reference)
.LBB0_14:
	s_or_b64 exec, exec, s[4:5]
	s_load_dwordx16 s[12:27], s[0:1], 0x40
	s_load_dwordx16 s[36:51], s[0:1], 0x80
	s_load_dwordx16 s[56:71], s[0:1], 0x240
	s_waitcnt lgkmcnt(0)
	v_writelane_b32 v253, s36, 51
	s_nop 1
	v_writelane_b32 v253, s37, 52
	v_writelane_b32 v253, s38, 53
	v_writelane_b32 v253, s39, 54
	v_writelane_b32 v253, s40, 55
	v_writelane_b32 v253, s41, 56
	v_writelane_b32 v253, s42, 57
	v_writelane_b32 v253, s43, 58
	v_writelane_b32 v253, s44, 59
	v_writelane_b32 v253, s45, 60
	v_writelane_b32 v253, s46, 61
	v_writelane_b32 v251, s49, 0
	v_writelane_b32 v253, s47, 62
	v_writelane_b32 v251, s50, 1
	v_writelane_b32 v253, s48, 63
	v_writelane_b32 v251, s51, 2
	s_load_dwordx16 s[36:51], s[0:1], 0xc0
	s_waitcnt lgkmcnt(0)
	v_writelane_b32 v251, s36, 3
	s_nop 1
	v_writelane_b32 v251, s37, 4
	v_writelane_b32 v251, s38, 5
	v_writelane_b32 v251, s39, 6
	v_writelane_b32 v251, s40, 7
	v_writelane_b32 v251, s41, 8
	v_writelane_b32 v251, s42, 9
	v_writelane_b32 v251, s43, 10
	v_writelane_b32 v251, s44, 11
	v_writelane_b32 v251, s45, 12
	v_writelane_b32 v251, s46, 13
	v_writelane_b32 v251, s47, 14
	v_writelane_b32 v251, s48, 15
	v_writelane_b32 v251, s49, 16
	v_writelane_b32 v251, s50, 17
	v_writelane_b32 v251, s51, 18
	s_load_dwordx16 s[36:51], s[0:1], 0x1a0
	s_waitcnt lgkmcnt(0)
	v_writelane_b32 v251, s36, 19
	s_nop 1
	v_writelane_b32 v251, s37, 20
	v_writelane_b32 v251, s38, 21
	v_writelane_b32 v251, s39, 22
	v_writelane_b32 v251, s40, 23
	v_writelane_b32 v251, s41, 24
	v_writelane_b32 v251, s42, 25
	v_writelane_b32 v251, s43, 26
	v_writelane_b32 v251, s44, 27
	v_writelane_b32 v251, s45, 28
	v_writelane_b32 v251, s46, 29
	v_writelane_b32 v251, s47, 30
	v_writelane_b32 v251, s48, 31
	v_writelane_b32 v251, s49, 32
	v_writelane_b32 v251, s50, 33
	v_writelane_b32 v251, s51, 34
	s_load_dwordx16 s[36:51], s[0:1], 0x1e0
	s_mov_b64 s[0:1], 0x82000
	v_cmp_gt_u64_e32 vcc, s[0:1], v[8:9]
	s_waitcnt lgkmcnt(0)
	v_writelane_b32 v251, s36, 35
	s_nop 1
	v_writelane_b32 v251, s37, 36
	v_writelane_b32 v251, s38, 37
	v_writelane_b32 v251, s39, 38
	v_writelane_b32 v251, s40, 39
	v_writelane_b32 v251, s41, 40
	v_writelane_b32 v251, s42, 41
	v_writelane_b32 v251, s43, 42
	v_writelane_b32 v251, s44, 43
	v_writelane_b32 v251, s45, 44
	v_writelane_b32 v251, s46, 45
	v_writelane_b32 v251, s47, 46
	v_writelane_b32 v251, s48, 47
	v_writelane_b32 v251, s49, 48
	v_writelane_b32 v251, s50, 49
	v_writelane_b32 v251, s51, 50
	s_and_saveexec_b64 s[0:1], vcc
	s_cbranch_execz .LBB0_23
	v_and_b32_e32 v2, 0xf8, v1
	v_readlane_b32 s36, v253, 0
	v_mov_b32_e32 v11, 0
	v_lshlrev_b32_e32 v10, 1, v2
	v_readlane_b32 s50, v253, 14
	v_readlane_b32 s51, v253, 15
	s_mov_b32 s6, 0xffc00000
	s_mov_b64 s[4:5], 0
	v_lshl_add_u64 v[12:13], s[50:51], 0, v[10:11]
	s_movk_i32 s7, 0xff
	v_lshlrev_b32_e32 v10, 2, v2
	s_movk_i32 s30, 0x7fff
	v_mov_b32_e32 v1, 1
	v_readlane_b32 s37, v253, 1
	v_readlane_b32 s38, v253, 2
	v_readlane_b32 s39, v253, 3
	v_readlane_b32 s40, v253, 4
	v_readlane_b32 s41, v253, 5
	v_readlane_b32 s42, v253, 6
	v_readlane_b32 s43, v253, 7
	v_readlane_b32 s44, v253, 8
	v_readlane_b32 s45, v253, 9
	v_readlane_b32 s46, v253, 10
	v_readlane_b32 s47, v253, 11
	v_readlane_b32 s48, v253, 12
	v_readlane_b32 s49, v253, 13
	s_cmp_lg_u32 s88, 0x100
	s_cbranch_scc1 .Lp0p_skip
	v_readlane_b32 s72, v253, 46
	v_readlane_b32 s73, v253, 47
	v_readlane_b32 s74, v253, 14
	v_readlane_b32 s75, v253, 15
	v_lshlrev_b64 v[204:205], 5, v[8:9]
	v_lshlrev_b64 v[206:207], 4, v[8:9]
	s_mov_b64 s[76:77], 0x400000
	s_mov_b64 s[78:79], 0x200000
	v_lshl_add_u64 v[204:205], v[204:205], 0, s[72:73]
	v_lshl_add_u64 v[206:207], v[206:207], 0, s[74:75]
	global_load_dwordx4 v[160:163], v[204:205], off
	global_load_dwordx4 v[164:167], v[204:205], off offset:16
	v_lshl_add_u64 v[204:205], v[204:205], 0, s[76:77]
	global_load_dwordx4 v[168:171], v[204:205], off
	global_load_dwordx4 v[172:175], v[204:205], off offset:16
	v_lshl_add_u64 v[204:205], v[204:205], 0, s[76:77]
	global_load_dwordx4 v[176:179], v[204:205], off
	global_load_dwordx4 v[180:183], v[204:205], off offset:16
	v_lshl_add_u64 v[204:205], v[204:205], 0, s[76:77]
	global_load_dwordx4 v[184:187], v[204:205], off
	global_load_dwordx4 v[188:191], v[204:205], off offset:16
	v_lshl_add_u64 v[204:205], v[204:205], 0, s[76:77]
	s_waitcnt vmcnt(6)
	v_and_b32_sdwa v192, v160, v1 dst_sel:DWORD dst_unused:UNUSED_PAD src0_sel:WORD_1 src1_sel:DWORD
	v_and_b32_sdwa v193, v161, v1 dst_sel:DWORD dst_unused:UNUSED_PAD src0_sel:WORD_1 src1_sel:DWORD
	v_and_b32_sdwa v194, v162, v1 dst_sel:DWORD dst_unused:UNUSED_PAD src0_sel:WORD_1 src1_sel:DWORD
	v_and_b32_sdwa v195, v163, v1 dst_sel:DWORD dst_unused:UNUSED_PAD src0_sel:WORD_1 src1_sel:DWORD
	v_and_b32_sdwa v196, v164, v1 dst_sel:DWORD dst_unused:UNUSED_PAD src0_sel:WORD_1 src1_sel:DWORD
	v_and_b32_sdwa v197, v165, v1 dst_sel:DWORD dst_unused:UNUSED_PAD src0_sel:WORD_1 src1_sel:DWORD
	v_and_b32_sdwa v198, v166, v1 dst_sel:DWORD dst_unused:UNUSED_PAD src0_sel:WORD_1 src1_sel:DWORD
	v_and_b32_sdwa v199, v167, v1 dst_sel:DWORD dst_unused:UNUSED_PAD src0_sel:WORD_1 src1_sel:DWORD
	v_add3_u32 v160, v160, v192, s30
	v_add3_u32 v161, v161, v193, s30
	v_add3_u32 v162, v162, v194, s30
	v_add3_u32 v163, v163, v195, s30
	v_add3_u32 v164, v164, v196, s30
	v_add3_u32 v165, v165, v197, s30
	v_add3_u32 v166, v166, v198, s30
	v_add3_u32 v167, v167, v199, s30
	v_and_b32_e32 v192, 0xffff0000, v161
	v_and_b32_e32 v193, 0xffff0000, v163
	v_and_b32_e32 v194, 0xffff0000, v165
	v_and_b32_e32 v195, 0xffff0000, v167
	v_or_b32_sdwa v200, v192, v160 dst_sel:DWORD dst_unused:UNUSED_PAD src0_sel:DWORD src1_sel:WORD_1
	v_or_b32_sdwa v201, v193, v162 dst_sel:DWORD dst_unused:UNUSED_PAD src0_sel:DWORD src1_sel:WORD_1
	v_or_b32_sdwa v202, v194, v164 dst_sel:DWORD dst_unused:UNUSED_PAD src0_sel:DWORD src1_sel:WORD_1
	v_or_b32_sdwa v203, v195, v166 dst_sel:DWORD dst_unused:UNUSED_PAD src0_sel:DWORD src1_sel:WORD_1
	global_store_dwordx4 v[206:207], v[200:203], off
	v_lshl_add_u64 v[206:207], v[206:207], 0, s[78:79]
	s_waitcnt vmcnt(5)
	v_and_b32_sdwa v192, v168, v1 dst_sel:DWORD dst_unused:UNUSED_PAD src0_sel:WORD_1 src1_sel:DWORD
	v_and_b32_sdwa v193, v169, v1 dst_sel:DWORD dst_unused:UNUSED_PAD src0_sel:WORD_1 src1_sel:DWORD
	v_and_b32_sdwa v194, v170, v1 dst_sel:DWORD dst_unused:UNUSED_PAD src0_sel:WORD_1 src1_sel:DWORD
	v_and_b32_sdwa v195, v171, v1 dst_sel:DWORD dst_unused:UNUSED_PAD src0_sel:WORD_1 src1_sel:DWORD
	v_and_b32_sdwa v196, v172, v1 dst_sel:DWORD dst_unused:UNUSED_PAD src0_sel:WORD_1 src1_sel:DWORD
	v_and_b32_sdwa v197, v173, v1 dst_sel:DWORD dst_unused:UNUSED_PAD src0_sel:WORD_1 src1_sel:DWORD
	v_and_b32_sdwa v198, v174, v1 dst_sel:DWORD dst_unused:UNUSED_PAD src0_sel:WORD_1 src1_sel:DWORD
	v_and_b32_sdwa v199, v175, v1 dst_sel:DWORD dst_unused:UNUSED_PAD src0_sel:WORD_1 src1_sel:DWORD
	v_add3_u32 v168, v168, v192, s30
	v_add3_u32 v169, v169, v193, s30
	v_add3_u32 v170, v170, v194, s30
	v_add3_u32 v171, v171, v195, s30
	v_add3_u32 v172, v172, v196, s30
	v_add3_u32 v173, v173, v197, s30
	v_add3_u32 v174, v174, v198, s30
	v_add3_u32 v175, v175, v199, s30
	v_and_b32_e32 v192, 0xffff0000, v169
	v_and_b32_e32 v193, 0xffff0000, v171
	v_and_b32_e32 v194, 0xffff0000, v173
	v_and_b32_e32 v195, 0xffff0000, v175
	v_or_b32_sdwa v200, v192, v168 dst_sel:DWORD dst_unused:UNUSED_PAD src0_sel:DWORD src1_sel:WORD_1
	v_or_b32_sdwa v201, v193, v170 dst_sel:DWORD dst_unused:UNUSED_PAD src0_sel:DWORD src1_sel:WORD_1
	v_or_b32_sdwa v202, v194, v172 dst_sel:DWORD dst_unused:UNUSED_PAD src0_sel:DWORD src1_sel:WORD_1
	v_or_b32_sdwa v203, v195, v174 dst_sel:DWORD dst_unused:UNUSED_PAD src0_sel:DWORD src1_sel:WORD_1
	global_store_dwordx4 v[206:207], v[200:203], off
	v_lshl_add_u64 v[206:207], v[206:207], 0, s[78:79]
	s_waitcnt vmcnt(4)
	v_and_b32_sdwa v192, v176, v1 dst_sel:DWORD dst_unused:UNUSED_PAD src0_sel:WORD_1 src1_sel:DWORD
	v_and_b32_sdwa v193, v177, v1 dst_sel:DWORD dst_unused:UNUSED_PAD src0_sel:WORD_1 src1_sel:DWORD
	v_and_b32_sdwa v194, v178, v1 dst_sel:DWORD dst_unused:UNUSED_PAD src0_sel:WORD_1 src1_sel:DWORD
	v_and_b32_sdwa v195, v179, v1 dst_sel:DWORD dst_unused:UNUSED_PAD src0_sel:WORD_1 src1_sel:DWORD
	v_and_b32_sdwa v196, v180, v1 dst_sel:DWORD dst_unused:UNUSED_PAD src0_sel:WORD_1 src1_sel:DWORD
	v_and_b32_sdwa v197, v181, v1 dst_sel:DWORD dst_unused:UNUSED_PAD src0_sel:WORD_1 src1_sel:DWORD
	v_and_b32_sdwa v198, v182, v1 dst_sel:DWORD dst_unused:UNUSED_PAD src0_sel:WORD_1 src1_sel:DWORD
	v_and_b32_sdwa v199, v183, v1 dst_sel:DWORD dst_unused:UNUSED_PAD src0_sel:WORD_1 src1_sel:DWORD
	v_add3_u32 v176, v176, v192, s30
	v_add3_u32 v177, v177, v193, s30
	v_add3_u32 v178, v178, v194, s30
	v_add3_u32 v179, v179, v195, s30
	v_add3_u32 v180, v180, v196, s30
	v_add3_u32 v181, v181, v197, s30
	v_add3_u32 v182, v182, v198, s30
	v_add3_u32 v183, v183, v199, s30
	v_and_b32_e32 v192, 0xffff0000, v177
	v_and_b32_e32 v193, 0xffff0000, v179
	v_and_b32_e32 v194, 0xffff0000, v181
	v_and_b32_e32 v195, 0xffff0000, v183
	v_or_b32_sdwa v200, v192, v176 dst_sel:DWORD dst_unused:UNUSED_PAD src0_sel:DWORD src1_sel:WORD_1
	v_or_b32_sdwa v201, v193, v178 dst_sel:DWORD dst_unused:UNUSED_PAD src0_sel:DWORD src1_sel:WORD_1
	v_or_b32_sdwa v202, v194, v180 dst_sel:DWORD dst_unused:UNUSED_PAD src0_sel:DWORD src1_sel:WORD_1
	v_or_b32_sdwa v203, v195, v182 dst_sel:DWORD dst_unused:UNUSED_PAD src0_sel:DWORD src1_sel:WORD_1
	global_store_dwordx4 v[206:207], v[200:203], off
	v_lshl_add_u64 v[206:207], v[206:207], 0, s[78:79]
	s_waitcnt vmcnt(3)
	v_and_b32_sdwa v192, v184, v1 dst_sel:DWORD dst_unused:UNUSED_PAD src0_sel:WORD_1 src1_sel:DWORD
	v_and_b32_sdwa v193, v185, v1 dst_sel:DWORD dst_unused:UNUSED_PAD src0_sel:WORD_1 src1_sel:DWORD
	v_and_b32_sdwa v194, v186, v1 dst_sel:DWORD dst_unused:UNUSED_PAD src0_sel:WORD_1 src1_sel:DWORD
	v_and_b32_sdwa v195, v187, v1 dst_sel:DWORD dst_unused:UNUSED_PAD src0_sel:WORD_1 src1_sel:DWORD
	v_and_b32_sdwa v196, v188, v1 dst_sel:DWORD dst_unused:UNUSED_PAD src0_sel:WORD_1 src1_sel:DWORD
	v_and_b32_sdwa v197, v189, v1 dst_sel:DWORD dst_unused:UNUSED_PAD src0_sel:WORD_1 src1_sel:DWORD
	v_and_b32_sdwa v198, v190, v1 dst_sel:DWORD dst_unused:UNUSED_PAD src0_sel:WORD_1 src1_sel:DWORD
	v_and_b32_sdwa v199, v191, v1 dst_sel:DWORD dst_unused:UNUSED_PAD src0_sel:WORD_1 src1_sel:DWORD
	v_add3_u32 v184, v184, v192, s30
	v_add3_u32 v185, v185, v193, s30
	v_add3_u32 v186, v186, v194, s30
	v_add3_u32 v187, v187, v195, s30
	v_add3_u32 v188, v188, v196, s30
	v_add3_u32 v189, v189, v197, s30
	v_add3_u32 v190, v190, v198, s30
	v_add3_u32 v191, v191, v199, s30
	v_and_b32_e32 v192, 0xffff0000, v185
	v_and_b32_e32 v193, 0xffff0000, v187
	v_and_b32_e32 v194, 0xffff0000, v189
	v_and_b32_e32 v195, 0xffff0000, v191
	v_or_b32_sdwa v200, v192, v184 dst_sel:DWORD dst_unused:UNUSED_PAD src0_sel:DWORD src1_sel:WORD_1
	v_or_b32_sdwa v201, v193, v186 dst_sel:DWORD dst_unused:UNUSED_PAD src0_sel:DWORD src1_sel:WORD_1
	v_or_b32_sdwa v202, v194, v188 dst_sel:DWORD dst_unused:UNUSED_PAD src0_sel:DWORD src1_sel:WORD_1
	v_or_b32_sdwa v203, v195, v190 dst_sel:DWORD dst_unused:UNUSED_PAD src0_sel:DWORD src1_sel:WORD_1
	global_store_dwordx4 v[206:207], v[200:203], off
	v_lshl_add_u64 v[206:207], v[206:207], 0, s[78:79]
	s_mov_b64 s[76:77], 0x80000
	v_lshl_add_u64 v[8:9], v[8:9], 0, s[76:77]
	s_mov_b64 s[76:77], 0x82000
	v_cmp_gt_u64_e32 vcc, s[76:77], v[8:9]
	s_nop 1
	s_and_b64 exec, exec, vcc
	s_cbranch_execz .LBB0_23
.Lp0p_skip:
	s_branch .LBB0_18
.LBB0_16:
	s_or_b64 exec, exec, s[10:11]
	v_lshl_add_u64 v[16:17], v[2:3], 0, v[10:11]
	global_load_dwordx4 v[2:5], v[16:17], off
	s_nop 0
	global_load_dwordx4 v[16:19], v[16:17], off offset:16
	s_waitcnt vmcnt(1)
	v_and_b32_sdwa v7, v4, v1 dst_sel:DWORD dst_unused:UNUSED_PAD src0_sel:WORD_1 src1_sel:DWORD
	v_and_b32_sdwa v21, v5, v1 dst_sel:DWORD dst_unused:UNUSED_PAD src0_sel:WORD_1 src1_sel:DWORD
	v_and_b32_sdwa v22, v3, v1 dst_sel:DWORD dst_unused:UNUSED_PAD src0_sel:WORD_1 src1_sel:DWORD
	s_waitcnt vmcnt(0)
	v_and_b32_sdwa v23, v18, v1 dst_sel:DWORD dst_unused:UNUSED_PAD src0_sel:WORD_1 src1_sel:DWORD
	v_and_b32_sdwa v24, v16, v1 dst_sel:DWORD dst_unused:UNUSED_PAD src0_sel:WORD_1 src1_sel:DWORD
	v_and_b32_sdwa v25, v19, v1 dst_sel:DWORD dst_unused:UNUSED_PAD src0_sel:WORD_1 src1_sel:DWORD
	v_and_b32_sdwa v26, v17, v1 dst_sel:DWORD dst_unused:UNUSED_PAD src0_sel:WORD_1 src1_sel:DWORD
	v_and_b32_sdwa v20, v2, v1 dst_sel:DWORD dst_unused:UNUSED_PAD src0_sel:WORD_1 src1_sel:DWORD
	v_add3_u32 v4, v4, v7, s30
	v_add3_u32 v5, v5, v21, s30
	v_add3_u32 v3, v3, v22, s30
	v_add3_u32 v7, v16, v24, s30
	v_add3_u32 v16, v18, v23, s30
	v_add3_u32 v18, v19, v25, s30
	v_add3_u32 v17, v17, v26, s30
	v_add3_u32 v2, v2, v20, s30
	v_and_b32_e32 v5, 0xffff0000, v5
	v_and_b32_e32 v19, 0xffff0000, v3
	v_and_b32_e32 v18, 0xffff0000, v18
	v_and_b32_e32 v17, 0xffff0000, v17
	v_or_b32_sdwa v3, v5, v4 dst_sel:DWORD dst_unused:UNUSED_PAD src0_sel:DWORD src1_sel:WORD_1
	v_or_b32_sdwa v2, v19, v2 dst_sel:DWORD dst_unused:UNUSED_PAD src0_sel:DWORD src1_sel:WORD_1
	v_or_b32_sdwa v5, v18, v16 dst_sel:DWORD dst_unused:UNUSED_PAD src0_sel:DWORD src1_sel:WORD_1
	v_or_b32_sdwa v4, v17, v7 dst_sel:DWORD dst_unused:UNUSED_PAD src0_sel:DWORD src1_sel:WORD_1
